# v87 + gather sub-phase D lane layout changed so each row load/store instruction covers contiguous 1 KB (lane l owns columns 256q+4l..+3)
# speedup vs baseline: 1.0141x; 1.0141x over previous
.Lgy_D_4:
	v_lshrrev_b32_e32 v142, 6, v162
	v_readlane_b32 s2, v242, 0
	v_readlane_b32 s59, v241, 24
	v_readfirstlane_b32 s29, v142
	s_lshl_b32 s2, s2, 2
	s_add_u32 s54, s2, s29
	s_load_dwordx4 s[92:95], s[0:1], 0xc0
	s_load_dwordx2 s[88:89], s[0:1], 0x120
	v_lshlrev_b32_e32 v160, 4, v168
	v_lshlrev_b32_e32 v161, 3, v168
	v_readlane_b32 s8, v240, 12
	v_readlane_b32 s9, v240, 13
	v_readlane_b32 s10, v240, 14
	v_readlane_b32 s11, v240, 15
	v_readlane_b32 s12, v240, 3
	v_readlane_b32 s13, v240, 5
	s_waitcnt lgkmcnt(0)
	s_nop 4
	global_load_dwordx4 v[80:83], v160, s[8:9] offset:0
	global_load_dwordx4 v[84:87], v160, s[8:9] offset:1024
	global_load_dwordx4 v[88:91], v160, s[8:9] offset:2048
	global_load_dwordx4 v[92:95], v160, s[8:9] offset:3072
	global_load_dwordx4 v[96:99], v160, s[10:11] offset:0
	global_load_dwordx4 v[100:103], v160, s[10:11] offset:1024
	global_load_dwordx4 v[104:107], v160, s[10:11] offset:2048
	global_load_dwordx4 v[108:111], v160, s[10:11] offset:3072
	s_cmp_lt_u32 s54, 0x4200
	s_cbranch_scc0 .Lgy_Ddone_12
	s_cmp_lg_u32 s12, 0
	s_cbranch_scc0 .Lgy_Dlast_13
	s_min_u32 s15, s54, 0x41ff
	s_lshl_b32 s50, s15, 12
	s_add_u32 s52, s88, s50
	s_addc_u32 s53, s89, 0
	global_load_dwordx4 v[48:51], v160, s[52:53] offset:0
	global_load_dwordx4 v[52:55], v160, s[52:53] offset:1024
	global_load_dwordx4 v[56:59], v160, s[52:53] offset:2048
	global_load_dwordx4 v[60:63], v160, s[52:53] offset:3072
	s_cmp_lt_u32 s15, 0x2000
	s_cselect_b32 s14, 0, 1
	s_cmp_lt_u32 s15, 0x4000
	s_cselect_b32 s14, s14, 2
	s_add_u32 s16, s14, s13
	s_mul_i32 s16, s16, 0x6000
	s_add_u32 s46, s94, s16
	s_addc_u32 s47, s95, 0
	global_load_dwordx4 v[112:115], v160, s[46:47] offset:0
	global_load_dwordx4 v[116:119], v160, s[46:47] offset:1024
	global_load_dwordx4 v[120:123], v160, s[46:47] offset:2048
	global_load_dwordx4 v[124:127], v160, s[46:47] offset:3072
	s_add_u32 s46, s46, 0x1000
	s_addc_u32 s47, s47, 0
	global_load_dwordx4 v[130:133], v160, s[46:47] offset:0
	global_load_dwordx4 v[134:137], v160, s[46:47] offset:1024
	global_load_dwordx4 v[138:141], v160, s[46:47] offset:2048
	global_load_dwordx4 v[142:145], v160, s[46:47] offset:3072
.Lgy_Dtok_14:
	s_mov_b32 s2, s54
	s_add_u32 s99, s54, s59
	s_min_u32 s15, s99, 0x41ff
	s_lshl_b32 s50, s15, 12
	s_add_u32 s52, s88, s50
	s_addc_u32 s53, s89, 0
	global_load_dwordx4 v[0:3], v160, s[52:53] offset:0
	global_load_dwordx4 v[4:7], v160, s[52:53] offset:1024
	global_load_dwordx4 v[8:11], v160, s[52:53] offset:2048
	global_load_dwordx4 v[12:15], v160, s[52:53] offset:3072
	s_cmp_lt_u32 s15, 0x2000
	s_cselect_b32 s14, 0, 1
	s_cmp_lt_u32 s15, 0x4000
	s_cselect_b32 s14, s14, 2
	s_add_u32 s16, s14, s13
	s_mul_i32 s16, s16, 0x6000
	s_add_u32 s46, s94, s16
	s_addc_u32 s47, s95, 0
	global_load_dwordx4 v[16:19], v160, s[46:47] offset:0
	global_load_dwordx4 v[20:23], v160, s[46:47] offset:1024
	global_load_dwordx4 v[24:27], v160, s[46:47] offset:2048
	global_load_dwordx4 v[28:31], v160, s[46:47] offset:3072
	s_add_u32 s46, s46, 0x1000
	s_addc_u32 s47, s47, 0
	global_load_dwordx4 v[32:35], v160, s[46:47] offset:0
	global_load_dwordx4 v[36:39], v160, s[46:47] offset:1024
	global_load_dwordx4 v[40:43], v160, s[46:47] offset:2048
	global_load_dwordx4 v[44:47], v160, s[46:47] offset:3072
	s_waitcnt vmcnt(12)
	v_add_f32_e32 v146, v48, v49
	v_add_f32_e32 v146, v146, v50
	v_add_f32_e32 v146, v146, v51
	v_add_f32_e32 v146, v146, v52
	v_add_f32_e32 v146, v146, v53
	v_add_f32_e32 v146, v146, v54
	v_add_f32_e32 v146, v146, v55
	v_add_f32_e32 v146, v146, v56
	v_add_f32_e32 v146, v146, v57
	v_add_f32_e32 v146, v146, v58
	v_add_f32_e32 v146, v146, v59
	v_add_f32_e32 v146, v146, v60
	v_add_f32_e32 v146, v146, v61
	v_add_f32_e32 v146, v146, v62
	v_add_f32_e32 v146, v146, v63
	s_nop 1
	v_add_f32_dpp v146, v146, v146 quad_perm:[1,0,3,2] row_mask:0xf bank_mask:0xf
	s_nop 1
	v_add_f32_dpp v146, v146, v146 quad_perm:[2,3,0,1] row_mask:0xf bank_mask:0xf
	s_nop 1
	v_add_f32_dpp v146, v146, v146 row_half_mirror row_mask:0xf bank_mask:0xf
	s_nop 1
	v_add_f32_dpp v146, v146, v146 row_mirror row_mask:0xf bank_mask:0xf
	s_nop 1
	v_readlane_b32 s4, v146, 0
	v_readlane_b32 s5, v146, 16
	v_readlane_b32 s6, v146, 32
	v_readlane_b32 s7, v146, 48
	s_nop 1
	v_mov_b32_e32 v147, s4
	v_add_f32_e32 v147, s5, v147
	v_add_f32_e32 v147, s6, v147
	v_add_f32_e32 v147, s7, v147
	v_mul_f32_e32 v147, 0x3a800000, v147
	v_sub_f32_e32 v48, v48, v147
	v_sub_f32_e32 v49, v49, v147
	v_sub_f32_e32 v50, v50, v147
	v_sub_f32_e32 v51, v51, v147
	v_sub_f32_e32 v52, v52, v147
	v_sub_f32_e32 v53, v53, v147
	v_sub_f32_e32 v54, v54, v147
	v_sub_f32_e32 v55, v55, v147
	v_sub_f32_e32 v56, v56, v147
	v_sub_f32_e32 v57, v57, v147
	v_sub_f32_e32 v58, v58, v147
	v_sub_f32_e32 v59, v59, v147
	v_sub_f32_e32 v60, v60, v147
	v_sub_f32_e32 v61, v61, v147
	v_sub_f32_e32 v62, v62, v147
	v_sub_f32_e32 v63, v63, v147
	v_mul_f32_e32 v146, v48, v48
	v_mul_f32_e32 v148, v49, v49
	v_add_f32_e32 v146, v146, v148
	v_mul_f32_e32 v148, v50, v50
	v_add_f32_e32 v146, v146, v148
	v_mul_f32_e32 v148, v51, v51
	v_add_f32_e32 v146, v146, v148
	v_mul_f32_e32 v148, v52, v52
	v_add_f32_e32 v146, v146, v148
	v_mul_f32_e32 v148, v53, v53
	v_add_f32_e32 v146, v146, v148
	v_mul_f32_e32 v148, v54, v54
	v_add_f32_e32 v146, v146, v148
	v_mul_f32_e32 v148, v55, v55
	v_add_f32_e32 v146, v146, v148
	v_mul_f32_e32 v148, v56, v56
	v_add_f32_e32 v146, v146, v148
	v_mul_f32_e32 v148, v57, v57
	v_add_f32_e32 v146, v146, v148
	v_mul_f32_e32 v148, v58, v58
	v_add_f32_e32 v146, v146, v148
	v_mul_f32_e32 v148, v59, v59
	v_add_f32_e32 v146, v146, v148
	v_mul_f32_e32 v148, v60, v60
	v_add_f32_e32 v146, v146, v148
	v_mul_f32_e32 v148, v61, v61
	v_add_f32_e32 v146, v146, v148
	v_mul_f32_e32 v148, v62, v62
	v_add_f32_e32 v146, v146, v148
	v_mul_f32_e32 v148, v63, v63
	v_add_f32_e32 v146, v146, v148
	s_nop 1
	v_add_f32_dpp v146, v146, v146 quad_perm:[1,0,3,2] row_mask:0xf bank_mask:0xf
	s_nop 1
	v_add_f32_dpp v146, v146, v146 quad_perm:[2,3,0,1] row_mask:0xf bank_mask:0xf
	s_nop 1
	v_add_f32_dpp v146, v146, v146 row_half_mirror row_mask:0xf bank_mask:0xf
	s_nop 1
	v_add_f32_dpp v146, v146, v146 row_mirror row_mask:0xf bank_mask:0xf
	s_nop 1
	v_readlane_b32 s4, v146, 0
	v_readlane_b32 s5, v146, 16
	v_readlane_b32 s6, v146, 32
	v_readlane_b32 s7, v146, 48
	s_nop 1
	v_mov_b32_e32 v147, s4
	v_add_f32_e32 v147, s5, v147
	v_add_f32_e32 v147, s6, v147
	v_add_f32_e32 v147, s7, v147
	v_fmamk_f32 v147, v147, 0x3a800000, v163
	s_mov_b32 s4, 0x800000
	v_cmp_gt_f32_e32 vcc, s4, v147
	v_mul_f32_e32 v148, 0x4b800000, v147
	s_nop 1
	v_cndmask_b32_e32 v147, v147, v148, vcc
	v_rsq_f32_e32 v147, v147
	s_nop 0
	v_mul_f32_e32 v148, 0x45800000, v147
	v_cndmask_b32_e32 v147, v147, v148, vcc
	v_mul_f32_e32 v48, v48, v147
	v_mul_f32_e32 v49, v49, v147
	v_mul_f32_e32 v50, v50, v147
	v_mul_f32_e32 v51, v51, v147
	v_mul_f32_e32 v52, v52, v147
	v_mul_f32_e32 v53, v53, v147
	v_mul_f32_e32 v54, v54, v147
	v_mul_f32_e32 v55, v55, v147
	v_mul_f32_e32 v56, v56, v147
	v_mul_f32_e32 v57, v57, v147
	v_mul_f32_e32 v58, v58, v147
	v_mul_f32_e32 v59, v59, v147
	v_mul_f32_e32 v60, v60, v147
	v_mul_f32_e32 v61, v61, v147
	v_mul_f32_e32 v62, v62, v147
	v_mul_f32_e32 v63, v63, v147
	v_fma_f32 v48, v80, v48, v96
	v_fma_f32 v49, v81, v49, v97
	v_fma_f32 v50, v82, v50, v98
	v_fma_f32 v51, v83, v51, v99
	v_fma_f32 v52, v84, v52, v100
	v_fma_f32 v53, v85, v53, v101
	v_fma_f32 v54, v86, v54, v102
	v_fma_f32 v55, v87, v55, v103
	v_fma_f32 v56, v88, v56, v104
	v_fma_f32 v57, v89, v57, v105
	v_fma_f32 v58, v90, v58, v106
	v_fma_f32 v59, v91, v59, v107
	v_fma_f32 v60, v92, v60, v108
	v_fma_f32 v61, v93, v61, v109
	v_fma_f32 v62, v94, v62, v110
	v_fma_f32 v63, v95, v63, v111
	s_lshl_b32 s50, s2, 12
	s_add_u32 s52, s70, s50
	s_addc_u32 s53, s71, 0
	global_store_dwordx4 v160, v[48:51], s[52:53] offset:0
	global_store_dwordx4 v160, v[52:55], s[52:53] offset:1024
	global_store_dwordx4 v160, v[56:59], s[52:53] offset:2048
	global_store_dwordx4 v160, v[60:63], s[52:53] offset:3072
	v_add_f32_e32 v130, 1.0, v130
	v_add_f32_e32 v131, 1.0, v131
	v_add_f32_e32 v132, 1.0, v132
	v_add_f32_e32 v133, 1.0, v133
	v_add_f32_e32 v134, 1.0, v134
	v_add_f32_e32 v135, 1.0, v135
	v_add_f32_e32 v136, 1.0, v136
	v_add_f32_e32 v137, 1.0, v137
	v_add_f32_e32 v138, 1.0, v138
	v_add_f32_e32 v139, 1.0, v139
	v_add_f32_e32 v140, 1.0, v140
	v_add_f32_e32 v141, 1.0, v141
	v_add_f32_e32 v142, 1.0, v142
	v_add_f32_e32 v143, 1.0, v143
	v_add_f32_e32 v144, 1.0, v144
	v_add_f32_e32 v145, 1.0, v145
	v_fma_f32 v112, v48, v130, v112
	v_fma_f32 v113, v49, v131, v113
	v_fma_f32 v114, v50, v132, v114
	v_fma_f32 v115, v51, v133, v115
	v_fma_f32 v116, v52, v134, v116
	v_fma_f32 v117, v53, v135, v117
	v_fma_f32 v118, v54, v136, v118
	v_fma_f32 v119, v55, v137, v119
	v_fma_f32 v120, v56, v138, v120
	v_fma_f32 v121, v57, v139, v121
	v_fma_f32 v122, v58, v140, v122
	v_fma_f32 v123, v59, v141, v123
	v_fma_f32 v124, v60, v142, v124
	v_fma_f32 v125, v61, v143, v125
	v_fma_f32 v126, v62, v144, v126
	v_fma_f32 v127, v63, v145, v127
	v_cvt_pk_bf16_f32 v64, v112, v113
	v_cvt_pk_bf16_f32 v65, v114, v115
	v_cvt_pk_bf16_f32 v66, v116, v117
	v_cvt_pk_bf16_f32 v67, v118, v119
	v_cvt_pk_bf16_f32 v68, v120, v121
	v_cvt_pk_bf16_f32 v69, v122, v123
	v_cvt_pk_bf16_f32 v70, v124, v125
	v_cvt_pk_bf16_f32 v71, v126, v127
	s_lshl_b32 s50, s2, 11
	s_add_u32 s46, s74, s50
	s_addc_u32 s47, s75, 0
	global_store_dwordx2 v161, v[64:65], s[46:47] offset:0
	global_store_dwordx2 v161, v[66:67], s[46:47] offset:512
	global_store_dwordx2 v161, v[68:69], s[46:47] offset:1024
	global_store_dwordx2 v161, v[70:71], s[46:47] offset:1536
	s_nop 1
	s_mov_b32 s54, s99
	s_cmp_lt_u32 s54, 0x4200
	s_cbranch_scc0 .Lgy_Dend_15
	s_mov_b32 s2, s54
	s_add_u32 s99, s54, s59
	s_min_u32 s15, s99, 0x41ff
	s_lshl_b32 s50, s15, 12
	s_add_u32 s52, s88, s50
	s_addc_u32 s53, s89, 0
	global_load_dwordx4 v[48:51], v160, s[52:53] offset:0
	global_load_dwordx4 v[52:55], v160, s[52:53] offset:1024
	global_load_dwordx4 v[56:59], v160, s[52:53] offset:2048
	global_load_dwordx4 v[60:63], v160, s[52:53] offset:3072
	s_cmp_lt_u32 s15, 0x2000
	s_cselect_b32 s14, 0, 1
	s_cmp_lt_u32 s15, 0x4000
	s_cselect_b32 s14, s14, 2
	s_add_u32 s16, s14, s13
	s_mul_i32 s16, s16, 0x6000
	s_add_u32 s46, s94, s16
	s_addc_u32 s47, s95, 0
	global_load_dwordx4 v[112:115], v160, s[46:47] offset:0
	global_load_dwordx4 v[116:119], v160, s[46:47] offset:1024
	global_load_dwordx4 v[120:123], v160, s[46:47] offset:2048
	global_load_dwordx4 v[124:127], v160, s[46:47] offset:3072
	s_add_u32 s46, s46, 0x1000
	s_addc_u32 s47, s47, 0
	global_load_dwordx4 v[130:133], v160, s[46:47] offset:0
	global_load_dwordx4 v[134:137], v160, s[46:47] offset:1024
	global_load_dwordx4 v[138:141], v160, s[46:47] offset:2048
	global_load_dwordx4 v[142:145], v160, s[46:47] offset:3072
	s_waitcnt vmcnt(12)
	v_add_f32_e32 v146, v0, v1
	v_add_f32_e32 v146, v146, v2
	v_add_f32_e32 v146, v146, v3
	v_add_f32_e32 v146, v146, v4
	v_add_f32_e32 v146, v146, v5
	v_add_f32_e32 v146, v146, v6
	v_add_f32_e32 v146, v146, v7
	v_add_f32_e32 v146, v146, v8
	v_add_f32_e32 v146, v146, v9
	v_add_f32_e32 v146, v146, v10
	v_add_f32_e32 v146, v146, v11
	v_add_f32_e32 v146, v146, v12
	v_add_f32_e32 v146, v146, v13
	v_add_f32_e32 v146, v146, v14
	v_add_f32_e32 v146, v146, v15
	s_nop 1
	v_add_f32_dpp v146, v146, v146 quad_perm:[1,0,3,2] row_mask:0xf bank_mask:0xf
	s_nop 1
	v_add_f32_dpp v146, v146, v146 quad_perm:[2,3,0,1] row_mask:0xf bank_mask:0xf
	s_nop 1
	v_add_f32_dpp v146, v146, v146 row_half_mirror row_mask:0xf bank_mask:0xf
	s_nop 1
	v_add_f32_dpp v146, v146, v146 row_mirror row_mask:0xf bank_mask:0xf
	s_nop 1
	v_readlane_b32 s4, v146, 0
	v_readlane_b32 s5, v146, 16
	v_readlane_b32 s6, v146, 32
	v_readlane_b32 s7, v146, 48
	s_nop 1
	v_mov_b32_e32 v147, s4
	v_add_f32_e32 v147, s5, v147
	v_add_f32_e32 v147, s6, v147
	v_add_f32_e32 v147, s7, v147
	v_mul_f32_e32 v147, 0x3a800000, v147
	v_sub_f32_e32 v0, v0, v147
	v_sub_f32_e32 v1, v1, v147
	v_sub_f32_e32 v2, v2, v147
	v_sub_f32_e32 v3, v3, v147
	v_sub_f32_e32 v4, v4, v147
	v_sub_f32_e32 v5, v5, v147
	v_sub_f32_e32 v6, v6, v147
	v_sub_f32_e32 v7, v7, v147
	v_sub_f32_e32 v8, v8, v147
	v_sub_f32_e32 v9, v9, v147
	v_sub_f32_e32 v10, v10, v147
	v_sub_f32_e32 v11, v11, v147
	v_sub_f32_e32 v12, v12, v147
	v_sub_f32_e32 v13, v13, v147
	v_sub_f32_e32 v14, v14, v147
	v_sub_f32_e32 v15, v15, v147
	v_mul_f32_e32 v146, v0, v0
	v_mul_f32_e32 v148, v1, v1
	v_add_f32_e32 v146, v146, v148
	v_mul_f32_e32 v148, v2, v2
	v_add_f32_e32 v146, v146, v148
	v_mul_f32_e32 v148, v3, v3
	v_add_f32_e32 v146, v146, v148
	v_mul_f32_e32 v148, v4, v4
	v_add_f32_e32 v146, v146, v148
	v_mul_f32_e32 v148, v5, v5
	v_add_f32_e32 v146, v146, v148
	v_mul_f32_e32 v148, v6, v6
	v_add_f32_e32 v146, v146, v148
	v_mul_f32_e32 v148, v7, v7
	v_add_f32_e32 v146, v146, v148
	v_mul_f32_e32 v148, v8, v8
	v_add_f32_e32 v146, v146, v148
	v_mul_f32_e32 v148, v9, v9
	v_add_f32_e32 v146, v146, v148
	v_mul_f32_e32 v148, v10, v10
	v_add_f32_e32 v146, v146, v148
	v_mul_f32_e32 v148, v11, v11
	v_add_f32_e32 v146, v146, v148
	v_mul_f32_e32 v148, v12, v12
	v_add_f32_e32 v146, v146, v148
	v_mul_f32_e32 v148, v13, v13
	v_add_f32_e32 v146, v146, v148
	v_mul_f32_e32 v148, v14, v14
	v_add_f32_e32 v146, v146, v148
	v_mul_f32_e32 v148, v15, v15
	v_add_f32_e32 v146, v146, v148
	s_nop 1
	v_add_f32_dpp v146, v146, v146 quad_perm:[1,0,3,2] row_mask:0xf bank_mask:0xf
	s_nop 1
	v_add_f32_dpp v146, v146, v146 quad_perm:[2,3,0,1] row_mask:0xf bank_mask:0xf
	s_nop 1
	v_add_f32_dpp v146, v146, v146 row_half_mirror row_mask:0xf bank_mask:0xf
	s_nop 1
	v_add_f32_dpp v146, v146, v146 row_mirror row_mask:0xf bank_mask:0xf
	s_nop 1
	v_readlane_b32 s4, v146, 0
	v_readlane_b32 s5, v146, 16
	v_readlane_b32 s6, v146, 32
	v_readlane_b32 s7, v146, 48
	s_nop 1
	v_mov_b32_e32 v147, s4
	v_add_f32_e32 v147, s5, v147
	v_add_f32_e32 v147, s6, v147
	v_add_f32_e32 v147, s7, v147
	v_fmamk_f32 v147, v147, 0x3a800000, v163
	s_mov_b32 s4, 0x800000
	v_cmp_gt_f32_e32 vcc, s4, v147
	v_mul_f32_e32 v148, 0x4b800000, v147
	s_nop 1
	v_cndmask_b32_e32 v147, v147, v148, vcc
	v_rsq_f32_e32 v147, v147
	s_nop 0
	v_mul_f32_e32 v148, 0x45800000, v147
	v_cndmask_b32_e32 v147, v147, v148, vcc
	v_mul_f32_e32 v0, v0, v147
	v_mul_f32_e32 v1, v1, v147
	v_mul_f32_e32 v2, v2, v147
	v_mul_f32_e32 v3, v3, v147
	v_mul_f32_e32 v4, v4, v147
	v_mul_f32_e32 v5, v5, v147
	v_mul_f32_e32 v6, v6, v147
	v_mul_f32_e32 v7, v7, v147
	v_mul_f32_e32 v8, v8, v147
	v_mul_f32_e32 v9, v9, v147
	v_mul_f32_e32 v10, v10, v147
	v_mul_f32_e32 v11, v11, v147
	v_mul_f32_e32 v12, v12, v147
	v_mul_f32_e32 v13, v13, v147
	v_mul_f32_e32 v14, v14, v147
	v_mul_f32_e32 v15, v15, v147
	v_fma_f32 v0, v80, v0, v96
	v_fma_f32 v1, v81, v1, v97
	v_fma_f32 v2, v82, v2, v98
	v_fma_f32 v3, v83, v3, v99
	v_fma_f32 v4, v84, v4, v100
	v_fma_f32 v5, v85, v5, v101
	v_fma_f32 v6, v86, v6, v102
	v_fma_f32 v7, v87, v7, v103
	v_fma_f32 v8, v88, v8, v104
	v_fma_f32 v9, v89, v9, v105
	v_fma_f32 v10, v90, v10, v106
	v_fma_f32 v11, v91, v11, v107
	v_fma_f32 v12, v92, v12, v108
	v_fma_f32 v13, v93, v13, v109
	v_fma_f32 v14, v94, v14, v110
	v_fma_f32 v15, v95, v15, v111
	s_lshl_b32 s50, s2, 12
	s_add_u32 s52, s70, s50
	s_addc_u32 s53, s71, 0
	global_store_dwordx4 v160, v[0:3], s[52:53] offset:0
	global_store_dwordx4 v160, v[4:7], s[52:53] offset:1024
	global_store_dwordx4 v160, v[8:11], s[52:53] offset:2048
	global_store_dwordx4 v160, v[12:15], s[52:53] offset:3072
	v_add_f32_e32 v32, 1.0, v32
	v_add_f32_e32 v33, 1.0, v33
	v_add_f32_e32 v34, 1.0, v34
	v_add_f32_e32 v35, 1.0, v35
	v_add_f32_e32 v36, 1.0, v36
	v_add_f32_e32 v37, 1.0, v37
	v_add_f32_e32 v38, 1.0, v38
	v_add_f32_e32 v39, 1.0, v39
	v_add_f32_e32 v40, 1.0, v40
	v_add_f32_e32 v41, 1.0, v41
	v_add_f32_e32 v42, 1.0, v42
	v_add_f32_e32 v43, 1.0, v43
	v_add_f32_e32 v44, 1.0, v44
	v_add_f32_e32 v45, 1.0, v45
	v_add_f32_e32 v46, 1.0, v46
	v_add_f32_e32 v47, 1.0, v47
	v_fma_f32 v16, v0, v32, v16
	v_fma_f32 v17, v1, v33, v17
	v_fma_f32 v18, v2, v34, v18
	v_fma_f32 v19, v3, v35, v19
	v_fma_f32 v20, v4, v36, v20
	v_fma_f32 v21, v5, v37, v21
	v_fma_f32 v22, v6, v38, v22
	v_fma_f32 v23, v7, v39, v23
	v_fma_f32 v24, v8, v40, v24
	v_fma_f32 v25, v9, v41, v25
	v_fma_f32 v26, v10, v42, v26
	v_fma_f32 v27, v11, v43, v27
	v_fma_f32 v28, v12, v44, v28
	v_fma_f32 v29, v13, v45, v29
	v_fma_f32 v30, v14, v46, v30
	v_fma_f32 v31, v15, v47, v31
	v_cvt_pk_bf16_f32 v64, v16, v17
	v_cvt_pk_bf16_f32 v65, v18, v19
	v_cvt_pk_bf16_f32 v66, v20, v21
	v_cvt_pk_bf16_f32 v67, v22, v23
	v_cvt_pk_bf16_f32 v68, v24, v25
	v_cvt_pk_bf16_f32 v69, v26, v27
	v_cvt_pk_bf16_f32 v70, v28, v29
	v_cvt_pk_bf16_f32 v71, v30, v31
	s_lshl_b32 s50, s2, 11
	s_add_u32 s46, s74, s50
	s_addc_u32 s47, s75, 0
	global_store_dwordx2 v161, v[64:65], s[46:47] offset:0
	global_store_dwordx2 v161, v[66:67], s[46:47] offset:512
	global_store_dwordx2 v161, v[68:69], s[46:47] offset:1024
	global_store_dwordx2 v161, v[70:71], s[46:47] offset:1536
	s_nop 1
	s_mov_b32 s54, s99
	s_cmp_lt_u32 s54, 0x4200
	s_cbranch_scc1 .Lgy_Dtok_14

.Lgy_Dlast_13:
	s_min_u32 s15, s54, 0x41ff
	s_lshl_b32 s50, s15, 12
	s_add_u32 s52, s88, s50
	s_addc_u32 s53, s89, 0
	global_load_dwordx4 v[48:51], v160, s[52:53] offset:0
	global_load_dwordx4 v[52:55], v160, s[52:53] offset:1024
	global_load_dwordx4 v[56:59], v160, s[52:53] offset:2048
	global_load_dwordx4 v[60:63], v160, s[52:53] offset:3072
.Lgy_Dtok_16:
	s_mov_b32 s2, s54
	s_add_u32 s99, s54, s59
	s_min_u32 s15, s99, 0x41ff
	s_lshl_b32 s50, s15, 12
	s_add_u32 s52, s88, s50
	s_addc_u32 s53, s89, 0
	global_load_dwordx4 v[0:3], v160, s[52:53] offset:0
	global_load_dwordx4 v[4:7], v160, s[52:53] offset:1024
	global_load_dwordx4 v[8:11], v160, s[52:53] offset:2048
	global_load_dwordx4 v[12:15], v160, s[52:53] offset:3072
	s_waitcnt vmcnt(4)
	v_add_f32_e32 v146, v48, v49
	v_add_f32_e32 v146, v146, v50
	v_add_f32_e32 v146, v146, v51
	v_add_f32_e32 v146, v146, v52
	v_add_f32_e32 v146, v146, v53
	v_add_f32_e32 v146, v146, v54
	v_add_f32_e32 v146, v146, v55
	v_add_f32_e32 v146, v146, v56
	v_add_f32_e32 v146, v146, v57
	v_add_f32_e32 v146, v146, v58
	v_add_f32_e32 v146, v146, v59
	v_add_f32_e32 v146, v146, v60
	v_add_f32_e32 v146, v146, v61
	v_add_f32_e32 v146, v146, v62
	v_add_f32_e32 v146, v146, v63
	s_nop 1
	v_add_f32_dpp v146, v146, v146 quad_perm:[1,0,3,2] row_mask:0xf bank_mask:0xf
	s_nop 1
	v_add_f32_dpp v146, v146, v146 quad_perm:[2,3,0,1] row_mask:0xf bank_mask:0xf
	s_nop 1
	v_add_f32_dpp v146, v146, v146 row_half_mirror row_mask:0xf bank_mask:0xf
	s_nop 1
	v_add_f32_dpp v146, v146, v146 row_mirror row_mask:0xf bank_mask:0xf
	s_nop 1
	v_readlane_b32 s4, v146, 0
	v_readlane_b32 s5, v146, 16
	v_readlane_b32 s6, v146, 32
	v_readlane_b32 s7, v146, 48
	s_nop 1
	v_mov_b32_e32 v147, s4
	v_add_f32_e32 v147, s5, v147
	v_add_f32_e32 v147, s6, v147
	v_add_f32_e32 v147, s7, v147
	v_mul_f32_e32 v147, 0x3a800000, v147
	v_sub_f32_e32 v48, v48, v147
	v_sub_f32_e32 v49, v49, v147
	v_sub_f32_e32 v50, v50, v147
	v_sub_f32_e32 v51, v51, v147
	v_sub_f32_e32 v52, v52, v147
	v_sub_f32_e32 v53, v53, v147
	v_sub_f32_e32 v54, v54, v147
	v_sub_f32_e32 v55, v55, v147
	v_sub_f32_e32 v56, v56, v147
	v_sub_f32_e32 v57, v57, v147
	v_sub_f32_e32 v58, v58, v147
	v_sub_f32_e32 v59, v59, v147
	v_sub_f32_e32 v60, v60, v147
	v_sub_f32_e32 v61, v61, v147
	v_sub_f32_e32 v62, v62, v147
	v_sub_f32_e32 v63, v63, v147
	v_mul_f32_e32 v146, v48, v48
	v_mul_f32_e32 v148, v49, v49
	v_add_f32_e32 v146, v146, v148
	v_mul_f32_e32 v148, v50, v50
	v_add_f32_e32 v146, v146, v148
	v_mul_f32_e32 v148, v51, v51
	v_add_f32_e32 v146, v146, v148
	v_mul_f32_e32 v148, v52, v52
	v_add_f32_e32 v146, v146, v148
	v_mul_f32_e32 v148, v53, v53
	v_add_f32_e32 v146, v146, v148
	v_mul_f32_e32 v148, v54, v54
	v_add_f32_e32 v146, v146, v148
	v_mul_f32_e32 v148, v55, v55
	v_add_f32_e32 v146, v146, v148
	v_mul_f32_e32 v148, v56, v56
	v_add_f32_e32 v146, v146, v148
	v_mul_f32_e32 v148, v57, v57
	v_add_f32_e32 v146, v146, v148
	v_mul_f32_e32 v148, v58, v58
	v_add_f32_e32 v146, v146, v148
	v_mul_f32_e32 v148, v59, v59
	v_add_f32_e32 v146, v146, v148
	v_mul_f32_e32 v148, v60, v60
	v_add_f32_e32 v146, v146, v148
	v_mul_f32_e32 v148, v61, v61
	v_add_f32_e32 v146, v146, v148
	v_mul_f32_e32 v148, v62, v62
	v_add_f32_e32 v146, v146, v148
	v_mul_f32_e32 v148, v63, v63
	v_add_f32_e32 v146, v146, v148
	s_nop 1
	v_add_f32_dpp v146, v146, v146 quad_perm:[1,0,3,2] row_mask:0xf bank_mask:0xf
	s_nop 1
	v_add_f32_dpp v146, v146, v146 quad_perm:[2,3,0,1] row_mask:0xf bank_mask:0xf
	s_nop 1
	v_add_f32_dpp v146, v146, v146 row_half_mirror row_mask:0xf bank_mask:0xf
	s_nop 1
	v_add_f32_dpp v146, v146, v146 row_mirror row_mask:0xf bank_mask:0xf
	s_nop 1
	v_readlane_b32 s4, v146, 0
	v_readlane_b32 s5, v146, 16
	v_readlane_b32 s6, v146, 32
	v_readlane_b32 s7, v146, 48
	s_nop 1
	v_mov_b32_e32 v147, s4
	v_add_f32_e32 v147, s5, v147
	v_add_f32_e32 v147, s6, v147
	v_add_f32_e32 v147, s7, v147
	v_fmamk_f32 v147, v147, 0x3a800000, v163
	s_mov_b32 s4, 0x800000
	v_cmp_gt_f32_e32 vcc, s4, v147
	v_mul_f32_e32 v148, 0x4b800000, v147
	s_nop 1
	v_cndmask_b32_e32 v147, v147, v148, vcc
	v_rsq_f32_e32 v147, v147
	s_nop 0
	v_mul_f32_e32 v148, 0x45800000, v147
	v_cndmask_b32_e32 v147, v147, v148, vcc
	v_mul_f32_e32 v48, v48, v147
	v_mul_f32_e32 v49, v49, v147
	v_mul_f32_e32 v50, v50, v147
	v_mul_f32_e32 v51, v51, v147
	v_mul_f32_e32 v52, v52, v147
	v_mul_f32_e32 v53, v53, v147
	v_mul_f32_e32 v54, v54, v147
	v_mul_f32_e32 v55, v55, v147
	v_mul_f32_e32 v56, v56, v147
	v_mul_f32_e32 v57, v57, v147
	v_mul_f32_e32 v58, v58, v147
	v_mul_f32_e32 v59, v59, v147
	v_mul_f32_e32 v60, v60, v147
	v_mul_f32_e32 v61, v61, v147
	v_mul_f32_e32 v62, v62, v147
	v_mul_f32_e32 v63, v63, v147
	v_fma_f32 v48, v80, v48, v96
	v_fma_f32 v49, v81, v49, v97
	v_fma_f32 v50, v82, v50, v98
	v_fma_f32 v51, v83, v51, v99
	v_fma_f32 v52, v84, v52, v100
	v_fma_f32 v53, v85, v53, v101
	v_fma_f32 v54, v86, v54, v102
	v_fma_f32 v55, v87, v55, v103
	v_fma_f32 v56, v88, v56, v104
	v_fma_f32 v57, v89, v57, v105
	v_fma_f32 v58, v90, v58, v106
	v_fma_f32 v59, v91, v59, v107
	v_fma_f32 v60, v92, v60, v108
	v_fma_f32 v61, v93, v61, v109
	v_fma_f32 v62, v94, v62, v110
	v_fma_f32 v63, v95, v63, v111
	s_lshl_b32 s50, s2, 12
	s_cmp_lt_u32 s2, 0x4000
	s_cbranch_scc0 .Lgy_stdone_18
	s_add_u32 s46, s92, s50
	s_addc_u32 s47, s93, 0
	global_store_dwordx4 v160, v[48:51], s[46:47] offset:0
	global_store_dwordx4 v160, v[52:55], s[46:47] offset:1024
	global_store_dwordx4 v160, v[56:59], s[46:47] offset:2048
	global_store_dwordx4 v160, v[60:63], s[46:47] offset:3072
.Lgy_stdone_18:
	s_nop 1
	s_mov_b32 s54, s99
	s_cmp_lt_u32 s54, 0x4200
	s_cbranch_scc0 .Lgy_Dend_17
	s_mov_b32 s2, s54
	s_add_u32 s99, s54, s59
	s_min_u32 s15, s99, 0x41ff
	s_lshl_b32 s50, s15, 12
	s_add_u32 s52, s88, s50
	s_addc_u32 s53, s89, 0
	global_load_dwordx4 v[48:51], v160, s[52:53] offset:0
	global_load_dwordx4 v[52:55], v160, s[52:53] offset:1024
	global_load_dwordx4 v[56:59], v160, s[52:53] offset:2048
	global_load_dwordx4 v[60:63], v160, s[52:53] offset:3072
	s_waitcnt vmcnt(4)
	v_add_f32_e32 v146, v0, v1
	v_add_f32_e32 v146, v146, v2
	v_add_f32_e32 v146, v146, v3
	v_add_f32_e32 v146, v146, v4
	v_add_f32_e32 v146, v146, v5
	v_add_f32_e32 v146, v146, v6
	v_add_f32_e32 v146, v146, v7
	v_add_f32_e32 v146, v146, v8
	v_add_f32_e32 v146, v146, v9
	v_add_f32_e32 v146, v146, v10
	v_add_f32_e32 v146, v146, v11
	v_add_f32_e32 v146, v146, v12
	v_add_f32_e32 v146, v146, v13
	v_add_f32_e32 v146, v146, v14
	v_add_f32_e32 v146, v146, v15
	s_nop 1
	v_add_f32_dpp v146, v146, v146 quad_perm:[1,0,3,2] row_mask:0xf bank_mask:0xf
	s_nop 1
	v_add_f32_dpp v146, v146, v146 quad_perm:[2,3,0,1] row_mask:0xf bank_mask:0xf
	s_nop 1
	v_add_f32_dpp v146, v146, v146 row_half_mirror row_mask:0xf bank_mask:0xf
	s_nop 1
	v_add_f32_dpp v146, v146, v146 row_mirror row_mask:0xf bank_mask:0xf
	s_nop 1
	v_readlane_b32 s4, v146, 0
	v_readlane_b32 s5, v146, 16
	v_readlane_b32 s6, v146, 32
	v_readlane_b32 s7, v146, 48
	s_nop 1
	v_mov_b32_e32 v147, s4
	v_add_f32_e32 v147, s5, v147
	v_add_f32_e32 v147, s6, v147
	v_add_f32_e32 v147, s7, v147
	v_mul_f32_e32 v147, 0x3a800000, v147
	v_sub_f32_e32 v0, v0, v147
	v_sub_f32_e32 v1, v1, v147
	v_sub_f32_e32 v2, v2, v147
	v_sub_f32_e32 v3, v3, v147
	v_sub_f32_e32 v4, v4, v147
	v_sub_f32_e32 v5, v5, v147
	v_sub_f32_e32 v6, v6, v147
	v_sub_f32_e32 v7, v7, v147
	v_sub_f32_e32 v8, v8, v147
	v_sub_f32_e32 v9, v9, v147
	v_sub_f32_e32 v10, v10, v147
	v_sub_f32_e32 v11, v11, v147
	v_sub_f32_e32 v12, v12, v147
	v_sub_f32_e32 v13, v13, v147
	v_sub_f32_e32 v14, v14, v147
	v_sub_f32_e32 v15, v15, v147
	v_mul_f32_e32 v146, v0, v0
	v_mul_f32_e32 v148, v1, v1
	v_add_f32_e32 v146, v146, v148
	v_mul_f32_e32 v148, v2, v2
	v_add_f32_e32 v146, v146, v148
	v_mul_f32_e32 v148, v3, v3
	v_add_f32_e32 v146, v146, v148
	v_mul_f32_e32 v148, v4, v4
	v_add_f32_e32 v146, v146, v148
	v_mul_f32_e32 v148, v5, v5
	v_add_f32_e32 v146, v146, v148
	v_mul_f32_e32 v148, v6, v6
	v_add_f32_e32 v146, v146, v148
	v_mul_f32_e32 v148, v7, v7
	v_add_f32_e32 v146, v146, v148
	v_mul_f32_e32 v148, v8, v8
	v_add_f32_e32 v146, v146, v148
	v_mul_f32_e32 v148, v9, v9
	v_add_f32_e32 v146, v146, v148
	v_mul_f32_e32 v148, v10, v10
	v_add_f32_e32 v146, v146, v148
	v_mul_f32_e32 v148, v11, v11
	v_add_f32_e32 v146, v146, v148
	v_mul_f32_e32 v148, v12, v12
	v_add_f32_e32 v146, v146, v148
	v_mul_f32_e32 v148, v13, v13
	v_add_f32_e32 v146, v146, v148
	v_mul_f32_e32 v148, v14, v14
	v_add_f32_e32 v146, v146, v148
	v_mul_f32_e32 v148, v15, v15
	v_add_f32_e32 v146, v146, v148
	s_nop 1
	v_add_f32_dpp v146, v146, v146 quad_perm:[1,0,3,2] row_mask:0xf bank_mask:0xf
	s_nop 1
	v_add_f32_dpp v146, v146, v146 quad_perm:[2,3,0,1] row_mask:0xf bank_mask:0xf
	s_nop 1
	v_add_f32_dpp v146, v146, v146 row_half_mirror row_mask:0xf bank_mask:0xf
	s_nop 1
	v_add_f32_dpp v146, v146, v146 row_mirror row_mask:0xf bank_mask:0xf
	s_nop 1
	v_readlane_b32 s4, v146, 0
	v_readlane_b32 s5, v146, 16
	v_readlane_b32 s6, v146, 32
	v_readlane_b32 s7, v146, 48
	s_nop 1
	v_mov_b32_e32 v147, s4
	v_add_f32_e32 v147, s5, v147
	v_add_f32_e32 v147, s6, v147
	v_add_f32_e32 v147, s7, v147
	v_fmamk_f32 v147, v147, 0x3a800000, v163
	s_mov_b32 s4, 0x800000
	v_cmp_gt_f32_e32 vcc, s4, v147
	v_mul_f32_e32 v148, 0x4b800000, v147
	s_nop 1
	v_cndmask_b32_e32 v147, v147, v148, vcc
	v_rsq_f32_e32 v147, v147
	s_nop 0
	v_mul_f32_e32 v148, 0x45800000, v147
	v_cndmask_b32_e32 v147, v147, v148, vcc
	v_mul_f32_e32 v0, v0, v147
	v_mul_f32_e32 v1, v1, v147
	v_mul_f32_e32 v2, v2, v147
	v_mul_f32_e32 v3, v3, v147
	v_mul_f32_e32 v4, v4, v147
	v_mul_f32_e32 v5, v5, v147
	v_mul_f32_e32 v6, v6, v147
	v_mul_f32_e32 v7, v7, v147
	v_mul_f32_e32 v8, v8, v147
	v_mul_f32_e32 v9, v9, v147
	v_mul_f32_e32 v10, v10, v147
	v_mul_f32_e32 v11, v11, v147
	v_mul_f32_e32 v12, v12, v147
	v_mul_f32_e32 v13, v13, v147
	v_mul_f32_e32 v14, v14, v147
	v_mul_f32_e32 v15, v15, v147
	v_fma_f32 v0, v80, v0, v96
	v_fma_f32 v1, v81, v1, v97
	v_fma_f32 v2, v82, v2, v98
	v_fma_f32 v3, v83, v3, v99
	v_fma_f32 v4, v84, v4, v100
	v_fma_f32 v5, v85, v5, v101
	v_fma_f32 v6, v86, v6, v102
	v_fma_f32 v7, v87, v7, v103
	v_fma_f32 v8, v88, v8, v104
	v_fma_f32 v9, v89, v9, v105
	v_fma_f32 v10, v90, v10, v106
	v_fma_f32 v11, v91, v11, v107
	v_fma_f32 v12, v92, v12, v108
	v_fma_f32 v13, v93, v13, v109
	v_fma_f32 v14, v94, v14, v110
	v_fma_f32 v15, v95, v15, v111
	s_lshl_b32 s50, s2, 12
	s_cmp_lt_u32 s2, 0x4000
	s_cbranch_scc0 .Lgy_stdone_19
	s_add_u32 s46, s92, s50
	s_addc_u32 s47, s93, 0
	global_store_dwordx4 v160, v[0:3], s[46:47] offset:0
	global_store_dwordx4 v160, v[4:7], s[46:47] offset:1024
	global_store_dwordx4 v160, v[8:11], s[46:47] offset:2048
	global_store_dwordx4 v160, v[12:15], s[46:47] offset:3072
